# stack + attention fast path laid out twice (one taken back edge per two tile pairs)
# baseline (speedup 1.0000x reference)
.Lattn_fair_0:
	s_cmp_lg_u32 s99, 0
	s_cbranch_scc0 .LBB0_452
	s_lshl_b32 s80, s10, 14
	v_add_u32_e32 v179, s80, v219
	v_add_u32_e32 v126, v179, v149
	ds_read_b128 v[102:105], v126 offset:49152
	ds_read_b128 v[118:121], v126 offset:53248
	ds_read_b128 v[122:125], v126 offset:57344
	ds_read_b128 v[228:231], v126 offset:61440
	s_add_i32 s63, s60, 0x80
	s_lshl_b32 s79, s62, 14
	s_cmp_ge_i32 s61, s48
	s_cselect_b32 s4, 0, 1
	s_waitcnt lgkmcnt(2)
	v_mfma_f32_32x32x16_bf16 v[50:65], v[102:105], v[98:101], v[50:65]
	v_exp_f32_e32 v66, v66
	v_exp_f32_e32 v249, v82
	v_add_u32_e32 v181, v179, v208
	ds_read_b128 v[102:105], v181 offset:49152
	v_mfma_f32_32x32x16_bf16 v[34:49], v[118:121], v[98:101], v[34:49]
	v_add_f32_e32 v254, 0, v66
	v_add_f32_e32 v255, 0, v249
	v_exp_f32_e32 v67, v67
	v_exp_f32_e32 v250, v83
	ds_read_b128 v[232:235], v181 offset:53248
	s_waitcnt lgkmcnt(2)
	v_mfma_f32_32x32x16_bf16 v[18:33], v[122:125], v[98:101], v[18:33]
	v_add_f32_e32 v254, v67, v254
	v_add_f32_e32 v255, v250, v255
	v_exp_f32_e32 v68, v68
	v_exp_f32_e32 v195, v84
	ds_read_b128 v[126:129], v181 offset:57344
	v_mfma_f32_32x32x16_bf16 v[2:17], v[228:231], v[98:101], v[2:17]
	v_add_f32_e32 v254, v68, v254
	v_add_f32_e32 v255, v195, v255
	v_exp_f32_e32 v69, v69
	v_exp_f32_e32 v251, v85
	ds_read_b128 v[118:121], v181 offset:61440
	s_waitcnt lgkmcnt(2)
	v_mfma_f32_32x32x16_bf16 v[50:65], v[102:105], v[106:109], v[50:65]
	v_add_f32_e32 v254, v69, v254
	v_add_f32_e32 v255, v251, v255
	v_exp_f32_e32 v70, v70
	v_exp_f32_e32 v252, v86
	v_add_u32_e32 v181, v179, v209
	ds_read_b128 v[122:125], v181 offset:49152
	v_mfma_f32_32x32x16_bf16 v[34:49], v[232:235], v[106:109], v[34:49]
	s_cbranch_scc1 .Lattn_u2_458
	s_add_i32 s82, s60, 0x100
	s_cmp_le_i32 s61, s39
	s_cselect_b32 s82, s63, s82
	s_lshl_b32 s82, s82, 12
	s_add_i32 s78, s79, 0xffffc000
	s_cmp_lg_u32 s62, 0
	s_cselect_b32 s78, s78, 0x8000
	v_lshl_add_u64 v[98:99], v[202:203], 0, s[82:83]
	s_add_i32 s78, s7, s78
	s_mov_b32 m0, s78
	v_lshl_add_u64 v[100:101], v[98:99], 0, s[30:31]
	global_load_lds_dwordx4 v[100:101], off
	s_add_i32 m0, s78, 0x2000
	v_lshl_add_u64 v[98:99], v[98:99], 0, s[36:37]
	global_load_lds_dwordx4 v[98:99], off
